# adds: it=0 norm loop with hoisted modulation loads; rope64 tables staged in 11 KiB static LDS for the QKV epilogue
# baseline (speedup 1.0000x reference)
.LBB0_181:
	s_min_i32 s8, s0, 0x4000
	s_ashr_i32 s8, s8, 11
	s_mul_i32 s20, s8, 0x2400
	s_ashr_i32 s21, s20, 31
	s_waitcnt vmcnt(0)
	v_pk_mul_f32 v[44:45], v[32:33], v[32:33]
	v_pk_mul_f32 v[48:49], v[30:31], v[30:31]
	s_lshl_b64 s[20:21], s[20:21], 2
	v_pk_mov_b32 v[50:51], v[48:49], v[44:45] op_sel:[1,0]
	v_mov_b32_e32 v49, v45
	s_add_u32 s20, s22, s20
	s_waitcnt vmcnt(2)
	v_pk_mul_f32 v[42:43], v[28:29], v[28:29]
	v_pk_mul_f32 v[46:47], v[26:27], v[26:27]
	v_pk_add_f32 v[44:45], v[50:51], v[48:49]
	s_addc_u32 s21, s23, s21
	v_pk_add_f32 v[50:51], v[44:45], v[44:45] op_sel_hi:[0,1]
	v_pk_mov_b32 v[44:45], v[46:47], v[42:43] op_sel:[1,0]
	v_mov_b32_e32 v47, v43
	v_pk_add_f32 v[42:43], v[44:45], v[46:47]
	v_lshl_add_u64 v[58:59], s[20:21], 0, v[12:13]
	v_pk_add_f32 v[52:53], v[42:43], v[42:43] op_sel_hi:[0,1]
	s_waitcnt vmcnt(1)
	v_mul_f32_e32 v42, v22, v22
	v_add_co_u32_e32 v46, vcc, s86, v58
	v_pk_fma_f32 v[54:55], v[22:23], v[22:23], v[42:43] op_sel_hi:[1,1,0]
	v_mul_f32_e32 v42, v24, v24
	v_addc_co_u32_e32 v47, vcc, 0, v59, vcc
	v_pk_fma_f32 v[56:57], v[24:25], v[24:25], v[42:43] op_sel_hi:[1,1,0]
	global_load_dwordx4 v[42:45], v12, s[20:21]
	s_nop 0
	global_load_dwordx4 v[68:71], v[46:47], off offset:1024
	global_load_dwordx4 v[76:79], v[46:47], off offset:2048
	global_load_dwordx4 v[84:87], v[46:47], off offset:3072
	global_load_dwordx4 v[64:67], v12, s[20:21] offset:1024
	global_load_dwordx4 v[72:75], v12, s[20:21] offset:2048
	global_load_dwordx4 v[80:83], v12, s[20:21] offset:3072
	global_load_dwordx4 v[46:49], v[46:47], off
	s_waitcnt vmcnt(2)
	v_mul_f32_e32 v54, v18, v18
	v_mul_f32_e32 v56, v19, v19
	v_mul_f32_e32 v50, v20, v20
	v_mul_f32_e32 v52, v21, v21
	v_pk_add_f32 v[54:55], v[54:55], v[56:57]
	v_pk_add_f32 v[50:51], v[50:51], v[52:53]
	s_lshl_b64 s[0:1], s[0:1], 11
	v_pk_add_f32 v[50:51], v[54:55], v[50:51]
	s_waitcnt vmcnt(0)
	v_pk_add_f32 v[48:49], v[48:49], 1.0 op_sel_hi:[1,0]
	v_add_f32_e32 v50, v50, v51
	ds_bpermute_b32 v51, v36, v50
	v_pk_add_f32 v[46:47], v[46:47], 1.0 op_sel_hi:[1,0]
	s_waitcnt lgkmcnt(0)
	v_add_f32_e32 v50, v50, v51
	ds_bpermute_b32 v51, v37, v50
	s_waitcnt lgkmcnt(0)
	v_add_f32_e32 v50, v50, v51
	ds_bpermute_b32 v51, v38, v50
	s_waitcnt lgkmcnt(0)
	v_add_f32_e32 v50, v50, v51
	ds_bpermute_b32 v51, v39, v50
	s_waitcnt lgkmcnt(0)
	v_add_f32_e32 v50, v50, v51
	ds_bpermute_b32 v51, v40, v50
	s_waitcnt lgkmcnt(0)
	v_add_f32_e32 v50, v50, v51
	ds_bpermute_b32 v51, v41, v50
	s_waitcnt lgkmcnt(0)
	v_add_f32_e32 v50, v50, v51
	v_fmamk_f32 v50, v50, 0x3a800000, v218
	v_mul_f32_e32 v51, 0x4f800000, v50
	v_cmp_gt_f32_e32 vcc, s85, v50
	s_nop 1
	v_cndmask_b32_e32 v52, v50, v51, vcc
	v_sqrt_f32_e32 v53, v52
	v_lshl_add_u64 v[50:51], v[34:35], 0, s[0:1]
	v_add_u32_e32 v54, -1, v53
	v_add_u32_e32 v55, 1, v53
	v_fma_f32 v56, -v54, v53, v52
	v_fma_f32 v57, -v55, v53, v52
	v_cmp_ge_f32_e64 s[0:1], 0, v56
	s_nop 1
	v_cndmask_b32_e64 v53, v53, v54, s[0:1]
	v_cmp_lt_f32_e64 s[0:1], 0, v57
	s_nop 1
	v_cndmask_b32_e64 v53, v53, v55, s[0:1]
	v_mul_f32_e32 v54, 0x37800000, v53
	v_cndmask_b32_e32 v53, v53, v54, vcc
	v_cmp_class_f32_e32 vcc, v52, v219
	s_nop 1
	v_cndmask_b32_e32 v54, v53, v52, vcc
	v_div_scale_f32 v55, s[0:1], v54, v54, 1.0
	v_rcp_f32_e32 v56, v55
	v_lshl_add_u64 v[52:53], v[58:59], 0, s[90:91]
	v_div_scale_f32 v57, vcc, 1.0, v54, 1.0
	v_fma_f32 v58, -v55, v56, 1.0
	v_fmac_f32_e32 v56, v58, v56
	v_mul_f32_e32 v58, v57, v56
	v_fma_f32 v59, -v55, v58, v57
	v_fmac_f32_e32 v58, v59, v56
	v_fma_f32 v55, -v55, v58, v57
	v_div_fmas_f32 v55, v55, v56, v58
	v_div_fixup_f32 v54, v55, v54, 1.0
	v_pk_mul_f32 v[30:31], v[30:31], v[54:55] op_sel_hi:[1,0]
	v_pk_mul_f32 v[32:33], v[32:33], v[54:55] op_sel_hi:[1,0]
	v_pk_fma_f32 v[30:31], v[46:47], v[30:31], v[42:43]
	v_pk_fma_f32 v[32:33], v[48:49], v[32:33], v[44:45]
	v_cvt_pk_bf16_f32 v30, v30, v31
	v_cvt_pk_bf16_f32 v31, v32, v33
	global_store_dwordx2 v[50:51], v[30:31], off
	v_mov_b64_e32 v[42:43], v[64:65]
	v_mov_b64_e32 v[44:45], v[66:67]
	v_mov_b64_e32 v[30:31], v[68:69]
	v_mov_b64_e32 v[32:33], v[70:71]
	v_pk_mul_f32 v[26:27], v[26:27], v[54:55] op_sel_hi:[1,0]
	v_pk_mul_f32 v[28:29], v[28:29], v[54:55] op_sel_hi:[1,0]
	v_pk_mul_f32 v[22:23], v[22:23], v[54:55] op_sel_hi:[1,0]
	v_pk_mul_f32 v[24:25], v[24:25], v[54:55] op_sel_hi:[1,0]
	v_pk_mul_f32 v[18:19], v[18:19], v[54:55] op_sel_hi:[1,0]
	v_pk_mul_f32 v[20:21], v[20:21], v[54:55] op_sel_hi:[1,0]
	s_andn2_b64 vcc, exec, s[18:19]
	v_pk_add_f32 v[32:33], v[32:33], 1.0 op_sel_hi:[1,0]
	v_pk_add_f32 v[30:31], v[30:31], 1.0 op_sel_hi:[1,0]
	v_pk_fma_f32 v[28:29], v[32:33], v[28:29], v[44:45]
	v_pk_fma_f32 v[26:27], v[30:31], v[26:27], v[42:43]
	v_mul_f32_e32 v42, v5, v5
	v_cvt_pk_bf16_f32 v26, v26, v27
	v_cvt_pk_bf16_f32 v27, v28, v29
	global_store_dwordx2 v[50:51], v[26:27], off offset:512
	v_mov_b64_e32 v[30:31], v[72:73]
	v_mov_b64_e32 v[32:33], v[74:75]
	v_mov_b64_e32 v[26:27], v[76:77]
	v_mov_b64_e32 v[28:29], v[78:79]
	v_mul_f32_e32 v43, v7, v7
	v_mul_f32_e32 v44, v1, v1
	v_mul_f32_e32 v45, v3, v3
	v_fmac_f32_e32 v42, v4, v4
	v_fmac_f32_e32 v43, v6, v6
	v_fmac_f32_e32 v44, v0, v0
	v_fmac_f32_e32 v45, v2, v2
	v_pk_add_f32 v[28:29], v[28:29], 1.0 op_sel_hi:[1,0]
	v_pk_add_f32 v[26:27], v[26:27], 1.0 op_sel_hi:[1,0]
	v_pk_fma_f32 v[24:25], v[24:25], v[28:29], v[32:33]
	v_pk_fma_f32 v[22:23], v[22:23], v[26:27], v[30:31]
	v_mul_f32_e32 v32, v9, v9
	v_cvt_pk_bf16_f32 v22, v22, v23
	v_cvt_pk_bf16_f32 v23, v24, v25
	global_store_dwordx2 v[50:51], v[22:23], off offset:1024
	v_mov_b64_e32 v[28:29], v[80:81]
	v_mov_b64_e32 v[30:31], v[82:83]
	v_mov_b64_e32 v[24:25], v[84:85]
	v_mov_b64_e32 v[26:27], v[86:87]
	v_mul_f32_e32 v22, v15, v15
	v_mul_f32_e32 v23, v17, v17
	v_mul_f32_e32 v33, v11, v11
	v_fmac_f32_e32 v22, v14, v14
	v_fmac_f32_e32 v23, v16, v16
	v_fmac_f32_e32 v32, v8, v8
	v_fmac_f32_e32 v33, v10, v10
	v_add_f32_e32 v22, v22, v23
	v_add_f32_e32 v23, v32, v33
	v_add_f32_e32 v32, v42, v43
	v_add_f32_e32 v22, v22, v23
	v_add_f32_e32 v33, v44, v45
	v_add_f32_e32 v22, v32, v22
	v_add_f32_e32 v22, v33, v22
	ds_bpermute_b32 v23, v36, v22
	s_waitcnt lgkmcnt(0)
	v_add_f32_e32 v22, v22, v23
	ds_bpermute_b32 v23, v37, v22
	s_waitcnt lgkmcnt(0)
	v_add_f32_e32 v22, v22, v23
	ds_bpermute_b32 v23, v38, v22
	s_waitcnt lgkmcnt(0)
	v_add_f32_e32 v22, v22, v23
	ds_bpermute_b32 v23, v39, v22
	s_waitcnt lgkmcnt(0)
	v_add_f32_e32 v22, v22, v23
	ds_bpermute_b32 v23, v40, v22
	s_waitcnt lgkmcnt(0)
	v_add_f32_e32 v22, v22, v23
	ds_bpermute_b32 v23, v41, v22
	v_pk_add_f32 v[26:27], v[26:27], 1.0 op_sel_hi:[1,0]
	v_pk_add_f32 v[24:25], v[24:25], 1.0 op_sel_hi:[1,0]
	v_pk_fma_f32 v[20:21], v[20:21], v[26:27], v[30:31]
	v_pk_fma_f32 v[18:19], v[18:19], v[24:25], v[28:29]
	s_nop 0
	v_cvt_pk_bf16_f32 v18, v18, v19
	v_cvt_pk_bf16_f32 v19, v20, v21
	global_store_dwordx2 v[50:51], v[18:19], off offset:1536
	s_cbranch_vccnz .LBB0_178
	s_min_i32 s0, s16, 0x4000
	s_ashr_i32 s0, s0, 11
	s_mulk_i32 s0, 0x2400
	s_ashr_i32 s1, s0, 31
	s_lshl_b64 s[0:1], s[0:1], 2
	s_add_u32 s18, s22, s0
	s_addc_u32 s19, s23, s1
	v_lshl_add_u64 v[28:29], s[18:19], 0, v[12:13]
	v_add_co_u32_e32 v18, vcc, s86, v28
	s_waitcnt lgkmcnt(0)
	v_add_f32_e32 v22, v22, v23
	v_addc_co_u32_e32 v19, vcc, 0, v29, vcc
	global_load_dwordx4 v[92:95], v[18:19], off offset:1024
	global_load_dwordx4 v[100:103], v[18:19], off offset:2048
	global_load_dwordx4 v[108:111], v[18:19], off offset:3072
	global_load_dwordx4 v[88:91], v12, s[18:19] offset:1024
	global_load_dwordx4 v[96:99], v12, s[18:19] offset:2048
	global_load_dwordx4 v[104:107], v12, s[18:19] offset:3072
	global_load_dwordx4 v[18:21], v[18:19], off
	s_nop 0
	global_load_dwordx4 v[24:27], v12, s[18:19]
	v_fmamk_f32 v22, v22, 0x3a800000, v218
	v_mul_f32_e32 v23, 0x4f800000, v22
	v_cmp_gt_f32_e32 vcc, s85, v22
	s_lshl_b64 s[0:1], s[16:17], 11
	v_lshl_add_u64 v[28:29], v[28:29], 0, s[90:91]
	v_cndmask_b32_e32 v30, v22, v23, vcc
	v_sqrt_f32_e32 v31, v30
	v_lshl_add_u64 v[22:23], v[34:35], 0, s[0:1]
	v_add_u32_e32 v32, -1, v31
	v_add_u32_e32 v33, 1, v31
	v_fma_f32 v42, -v32, v31, v30
	v_fma_f32 v43, -v33, v31, v30
	v_cmp_ge_f32_e64 s[0:1], 0, v42
	s_waitcnt vmcnt(1)
	v_pk_add_f32 v[20:21], v[20:21], 1.0 op_sel_hi:[1,0]
	v_cndmask_b32_e64 v31, v31, v32, s[0:1]
	v_cmp_lt_f32_e64 s[0:1], 0, v43
	v_pk_add_f32 v[18:19], v[18:19], 1.0 op_sel_hi:[1,0]
	s_nop 0
	v_cndmask_b32_e64 v31, v31, v33, s[0:1]
	v_mul_f32_e32 v32, 0x37800000, v31
	v_cndmask_b32_e32 v31, v31, v32, vcc
	v_cmp_class_f32_e32 vcc, v30, v219
	s_nop 1
	v_cndmask_b32_e32 v30, v31, v30, vcc
	v_div_scale_f32 v31, s[0:1], v30, v30, 1.0
	v_rcp_f32_e32 v32, v31
	v_div_scale_f32 v33, vcc, 1.0, v30, 1.0
	v_fma_f32 v42, -v31, v32, 1.0
	v_fmac_f32_e32 v32, v42, v32
	v_mul_f32_e32 v42, v33, v32
	v_fma_f32 v43, -v31, v42, v33
	v_fmac_f32_e32 v42, v43, v32
	v_fma_f32 v31, -v31, v42, v33
	v_div_fmas_f32 v31, v31, v32, v42
	v_div_fixup_f32 v30, v31, v30, 1.0
	v_pk_mul_f32 v[14:15], v[14:15], v[30:31] op_sel_hi:[1,0]
	v_pk_mul_f32 v[16:17], v[16:17], v[30:31] op_sel_hi:[1,0]
	s_waitcnt vmcnt(0)
	v_pk_fma_f32 v[14:15], v[14:15], v[18:19], v[24:25]
	v_pk_fma_f32 v[16:17], v[16:17], v[20:21], v[26:27]
	v_cvt_pk_bf16_f32 v14, v14, v15
	v_cvt_pk_bf16_f32 v15, v16, v17
	global_store_dwordx2 v[22:23], v[14:15], off
	v_mov_b64_e32 v[18:19], v[88:89]
	v_mov_b64_e32 v[20:21], v[90:91]
	v_mov_b64_e32 v[14:15], v[92:93]
	v_mov_b64_e32 v[16:17], v[94:95]
	v_pk_mul_f32 v[8:9], v[8:9], v[30:31] op_sel_hi:[1,0]
	v_pk_mul_f32 v[10:11], v[10:11], v[30:31] op_sel_hi:[1,0]
	v_pk_mul_f32 v[4:5], v[4:5], v[30:31] op_sel_hi:[1,0]
	v_pk_mul_f32 v[6:7], v[6:7], v[30:31] op_sel_hi:[1,0]
	v_pk_mul_f32 v[0:1], v[0:1], v[30:31] op_sel_hi:[1,0]
	v_pk_mul_f32 v[2:3], v[2:3], v[30:31] op_sel_hi:[1,0]
	v_pk_add_f32 v[16:17], v[16:17], 1.0 op_sel_hi:[1,0]
	v_pk_add_f32 v[14:15], v[14:15], 1.0 op_sel_hi:[1,0]
	v_pk_fma_f32 v[10:11], v[10:11], v[16:17], v[20:21]
	v_pk_fma_f32 v[8:9], v[8:9], v[14:15], v[18:19]
	s_nop 0
	v_cvt_pk_bf16_f32 v8, v8, v9
	v_cvt_pk_bf16_f32 v9, v10, v11
	global_store_dwordx2 v[22:23], v[8:9], off offset:512
	v_mov_b64_e32 v[14:15], v[96:97]
	v_mov_b64_e32 v[16:17], v[98:99]
	v_mov_b64_e32 v[8:9], v[100:101]
	v_mov_b64_e32 v[10:11], v[102:103]
	v_pk_add_f32 v[10:11], v[10:11], 1.0 op_sel_hi:[1,0]
	v_pk_add_f32 v[8:9], v[8:9], 1.0 op_sel_hi:[1,0]
	v_pk_fma_f32 v[6:7], v[6:7], v[10:11], v[16:17]
	v_pk_fma_f32 v[4:5], v[4:5], v[8:9], v[14:15]
	s_nop 0
	v_cvt_pk_bf16_f32 v4, v4, v5
	v_cvt_pk_bf16_f32 v5, v6, v7
	global_store_dwordx2 v[22:23], v[4:5], off offset:1024
	v_mov_b64_e32 v[8:9], v[104:105]
	v_mov_b64_e32 v[10:11], v[106:107]
	v_mov_b64_e32 v[4:5], v[108:109]
	v_mov_b64_e32 v[6:7], v[110:111]
	v_pk_add_f32 v[6:7], v[6:7], 1.0 op_sel_hi:[1,0]
	v_pk_add_f32 v[4:5], v[4:5], 1.0 op_sel_hi:[1,0]
	v_pk_fma_f32 v[2:3], v[2:3], v[6:7], v[10:11]
	v_pk_fma_f32 v[0:1], v[0:1], v[4:5], v[8:9]
	s_nop 0
	v_cvt_pk_bf16_f32 v0, v0, v1
	v_cvt_pk_bf16_f32 v1, v2, v3
	global_store_dwordx2 v[22:23], v[0:1], off offset:1536
	s_branch .LBB0_178

.LBB0_556:
	s_or_b64 exec, exec, s[0:1]
	v_readlane_b32 s0, v254, 11
	v_readlane_b32 s1, v254, 12
	s_mov_b32 s1, s67
	v_writelane_b32 v254, s0, 11
	s_waitcnt lgkmcnt(0)
	s_barrier
	s_load_dwordx2 s[100:101], s[76:77], 0xc8
	v_lshlrev_b32_e32 v144, 4, v216
	s_waitcnt lgkmcnt(0)
	s_add_u32 s100, s100, 0x10000
	s_addc_u32 s101, s101, 0
	global_load_dwordx4 v[140:143], v144, s[100:101]
	v_add_u32_e32 v145, 0x25400, v144
	s_sub_u32 s100, s100, 0x25400
	s_waitcnt vmcnt(0)
	ds_write_b128 v145, v[140:143]
	s_waitcnt lgkmcnt(0)
	s_barrier
	v_writelane_b32 v254, s1, 12
	s_mov_b64 s[0:1], s[76:77]
	s_load_dwordx2 s[10:11], s[0:1], 0xc8
	s_mov_b64 s[0:1], s[76:77]
	s_load_dwordx2 s[12:13], s[0:1], 0xc8
	s_mov_b32 s33, s78
	v_readlane_b32 s45, v254, 0
	s_mov_b64 s[0:1], s[76:77]
	s_load_dwordx2 s[18:19], s[0:1], 0xc8
	s_mov_b64 s[0:1], s[76:77]
	s_load_dwordx2 s[20:21], s[0:1], 0xc8
	s_mov_b64 s[0:1], s[76:77]
	s_load_dwordx2 s[4:5], s[0:1], 0xc8
	s_mov_b64 s[0:1], s[76:77]
	s_load_dwordx2 s[6:7], s[0:1], 0xc8
	s_mov_b64 s[0:1], s[76:77]
	s_load_dwordx2 s[2:3], s[0:1], 0x60
	s_mov_b64 s[0:1], s[76:77]
	s_load_dwordx2 s[14:15], s[0:1], 0x68
	s_cmpk_lt_i32 s45, 0x2d0
	s_cselect_b64 s[16:17], -1, 0
	s_ashr_i32 s50, s45, 31
	v_mov_b32_e32 v8, v216
	s_cmpk_gt_i32 s45, 0x2cf
	s_nop 0
	v_readfirstlane_b32 s22, v8
	s_cbranch_scc1 .LBB0_558
	s_lshr_b32 s0, s50, 29
	s_add_i32 s0, s45, s0
	s_ashr_i32 s1, s0, 3
	s_and_b32 s0, s0, -8
	s_sub_i32 s0, s45, s0
	s_cmp_lt_i32 s0, 0
	s_movk_i32 s8, 0x5b
	s_cselect_b32 s8, s8, 0x5a
	s_mul_i32 s0, s0, s8
	s_add_i32 s0, s0, s1
	s_mul_hi_i32 s1, s0, 0x66666667
	s_lshr_b32 s8, s1, 31
	s_ashr_i32 s1, s1, 5
	s_add_i32 s1, s1, s8
	s_lshl_b32 s8, s1, 3
	s_mulk_i32 s1, 0x50
	s_sub_i32 s0, s0, s1
	s_bfe_i32 s1, s0, 0x80000
	s_bfe_u32 s1, s1, 0x3000c
	s_add_i32 s1, s0, s1
	s_bfe_i32 s9, s1, 0x80000
	s_and_b32 s1, s1, 0xf8
	s_sub_i32 s0, s0, s1
	s_sext_i32_i16 s9, s9
	s_sext_i32_i8 s0, s0
	s_add_i32 s8, s8, s0
	s_ashr_i32 s0, s9, 3

.LBB0_597:
	s_andn2_b64 vcc, exec, s[46:47]
	s_cbranch_vccnz .LBB0_599
	s_ashr_i32 s46, s34, 2
	s_ashr_i32 s47, s46, 31
	v_lshl_add_u64 v[158:159], s[46:47], 2, v[190:191]
	v_subrev_u32_e32 v158, s100, v158
	ds_read_b128 v[154:157], v158
	ds_read_b128 v[170:173], v158 offset:4096
	s_waitcnt lgkmcnt(0)
	v_pk_mul_f32 v[158:159], v[168:169], v[172:173]
	v_pk_mul_f32 v[174:175], v[166:167], v[170:171]
	v_pk_fma_f32 v[160:161], v[164:165], v[156:157], v[158:159] neg_lo:[0,0,1] neg_hi:[0,0,1]
	v_pk_fma_f32 v[158:159], v[162:163], v[154:155], v[174:175] neg_lo:[0,0,1] neg_hi:[0,0,1]
	v_pk_mul_f32 v[164:165], v[164:165], v[172:173]
	v_pk_mul_f32 v[162:163], v[162:163], v[170:171]
	v_pk_fma_f32 v[156:157], v[168:169], v[156:157], v[164:165]
	v_pk_fma_f32 v[154:155], v[166:167], v[154:155], v[162:163]
	v_subrev_u32_e32 v245, s100, v192
	ds_read_b128 v[162:165], v245
	ds_read_b128 v[166:169], v245 offset:4096
	s_waitcnt lgkmcnt(0)
	v_pk_mul_f32 v[170:171], v[148:149], v[168:169]
	v_pk_mul_f32 v[174:175], v[146:147], v[166:167]
	v_pk_fma_f32 v[172:173], v[152:153], v[164:165], v[170:171] neg_lo:[0,0,1] neg_hi:[0,0,1]
	v_pk_fma_f32 v[170:171], v[150:151], v[162:163], v[174:175] neg_lo:[0,0,1] neg_hi:[0,0,1]
	v_pk_mul_f32 v[152:153], v[152:153], v[168:169]
	v_pk_mul_f32 v[150:151], v[150:151], v[166:167]
	v_pk_fma_f32 v[176:177], v[148:149], v[164:165], v[152:153]
	v_pk_fma_f32 v[174:175], v[146:147], v[162:163], v[150:151]

.LBB0_605:
	s_andn2_b64 vcc, exec, s[0:1]
	s_cbranch_vccnz .LBB0_607
	s_ashr_i32 s0, s34, 2
	s_ashr_i32 s1, s0, 31
	v_lshl_add_u64 v[158:159], s[0:1], 2, v[190:191]
	v_subrev_u32_e32 v158, s100, v158
	ds_read_b128 v[154:157], v158
	ds_read_b128 v[170:173], v158 offset:4096
	s_waitcnt lgkmcnt(0)
	v_pk_mul_f32 v[158:159], v[168:169], v[172:173]
	v_pk_mul_f32 v[174:175], v[166:167], v[170:171]
	v_pk_fma_f32 v[160:161], v[164:165], v[156:157], v[158:159] neg_lo:[0,0,1] neg_hi:[0,0,1]
	v_pk_fma_f32 v[158:159], v[162:163], v[154:155], v[174:175] neg_lo:[0,0,1] neg_hi:[0,0,1]
	v_pk_mul_f32 v[164:165], v[164:165], v[172:173]
	v_pk_mul_f32 v[162:163], v[162:163], v[170:171]
	v_pk_fma_f32 v[156:157], v[168:169], v[156:157], v[164:165]
	v_pk_fma_f32 v[154:155], v[166:167], v[154:155], v[162:163]
	v_subrev_u32_e32 v245, s100, v196
	ds_read_b128 v[162:165], v245
	ds_read_b128 v[166:169], v245 offset:4096
	s_waitcnt lgkmcnt(0)
	v_pk_mul_f32 v[170:171], v[148:149], v[168:169]
	v_pk_mul_f32 v[174:175], v[146:147], v[166:167]
	v_pk_fma_f32 v[172:173], v[152:153], v[164:165], v[170:171] neg_lo:[0,0,1] neg_hi:[0,0,1]
	v_pk_fma_f32 v[170:171], v[150:151], v[162:163], v[174:175] neg_lo:[0,0,1] neg_hi:[0,0,1]
	v_pk_mul_f32 v[152:153], v[152:153], v[168:169]
	v_pk_mul_f32 v[150:151], v[150:151], v[166:167]
	v_pk_fma_f32 v[176:177], v[148:149], v[164:165], v[152:153]
	v_pk_fma_f32 v[174:175], v[146:147], v[162:163], v[150:151]

.LBB0_614:
	s_ashr_i32 s0, s34, 2
	s_ashr_i32 s1, s0, 31
	v_lshl_add_u64 v[158:159], s[0:1], 2, v[190:191]
	v_subrev_u32_e32 v158, s100, v158
	ds_read_b128 v[154:157], v158
	ds_read_b128 v[170:173], v158 offset:4096
	s_waitcnt lgkmcnt(0)
	v_pk_mul_f32 v[158:159], v[168:169], v[172:173]
	v_pk_mul_f32 v[174:175], v[166:167], v[170:171]
	v_pk_fma_f32 v[160:161], v[164:165], v[156:157], v[158:159] neg_lo:[0,0,1] neg_hi:[0,0,1]
	v_pk_fma_f32 v[158:159], v[162:163], v[154:155], v[174:175] neg_lo:[0,0,1] neg_hi:[0,0,1]
	v_pk_mul_f32 v[164:165], v[164:165], v[172:173]
	v_pk_mul_f32 v[162:163], v[162:163], v[170:171]
	v_pk_fma_f32 v[156:157], v[168:169], v[156:157], v[164:165]
	v_pk_fma_f32 v[154:155], v[166:167], v[154:155], v[162:163]
	v_subrev_u32_e32 v245, s100, v200
	ds_read_b128 v[162:165], v245
	ds_read_b128 v[166:169], v245 offset:4096
	s_waitcnt lgkmcnt(0)
	v_pk_mul_f32 v[170:171], v[148:149], v[168:169]
	v_pk_mul_f32 v[174:175], v[146:147], v[166:167]
	v_pk_fma_f32 v[172:173], v[152:153], v[164:165], v[170:171] neg_lo:[0,0,1] neg_hi:[0,0,1]
	v_pk_fma_f32 v[170:171], v[150:151], v[162:163], v[174:175] neg_lo:[0,0,1] neg_hi:[0,0,1]
	v_pk_mul_f32 v[152:153], v[152:153], v[168:169]
	v_pk_mul_f32 v[150:151], v[150:151], v[166:167]
	v_pk_fma_f32 v[176:177], v[148:149], v[164:165], v[152:153]
	v_pk_fma_f32 v[174:175], v[146:147], v[162:163], v[150:151]

.LBB0_622:
	s_ashr_i32 s0, s34, 2
	s_ashr_i32 s1, s0, 31
	v_lshl_add_u64 v[158:159], s[0:1], 2, v[190:191]
	v_subrev_u32_e32 v158, s100, v158
	ds_read_b128 v[154:157], v158
	ds_read_b128 v[170:173], v158 offset:4096
	s_waitcnt lgkmcnt(0)
	v_pk_mul_f32 v[158:159], v[168:169], v[172:173]
	v_pk_mul_f32 v[174:175], v[166:167], v[170:171]
	v_pk_fma_f32 v[160:161], v[164:165], v[156:157], v[158:159] neg_lo:[0,0,1] neg_hi:[0,0,1]
	v_pk_fma_f32 v[158:159], v[162:163], v[154:155], v[174:175] neg_lo:[0,0,1] neg_hi:[0,0,1]
	v_pk_mul_f32 v[164:165], v[164:165], v[172:173]
	v_pk_mul_f32 v[162:163], v[162:163], v[170:171]
	v_pk_fma_f32 v[156:157], v[168:169], v[156:157], v[164:165]
	v_pk_fma_f32 v[154:155], v[166:167], v[154:155], v[162:163]
	v_subrev_u32_e32 v245, s100, v204
	ds_read_b128 v[162:165], v245
	ds_read_b128 v[166:169], v245 offset:4096
	s_waitcnt lgkmcnt(0)
	v_pk_mul_f32 v[170:171], v[148:149], v[168:169]
	v_pk_mul_f32 v[174:175], v[146:147], v[166:167]
	v_pk_fma_f32 v[172:173], v[152:153], v[164:165], v[170:171] neg_lo:[0,0,1] neg_hi:[0,0,1]
	v_pk_fma_f32 v[170:171], v[150:151], v[162:163], v[174:175] neg_lo:[0,0,1] neg_hi:[0,0,1]
	v_pk_mul_f32 v[152:153], v[152:153], v[168:169]
	v_pk_mul_f32 v[150:151], v[150:151], v[166:167]
	v_pk_fma_f32 v[176:177], v[148:149], v[164:165], v[152:153]
	v_pk_fma_f32 v[174:175], v[146:147], v[162:163], v[150:151]

.LBB0_629:
	s_andn2_b64 vcc, exec, s[0:1]
	s_cbranch_vccnz .LBB0_631
	s_ashr_i32 s0, s36, 2
	s_ashr_i32 s1, s0, 31
	v_lshl_add_u64 v[158:159], s[0:1], 2, v[190:191]
	v_subrev_u32_e32 v158, s100, v158
	ds_read_b128 v[154:157], v158
	ds_read_b128 v[170:173], v158 offset:4096
	s_waitcnt lgkmcnt(0)
	v_pk_mul_f32 v[158:159], v[168:169], v[172:173]
	v_pk_mul_f32 v[174:175], v[166:167], v[170:171]
	v_pk_fma_f32 v[160:161], v[164:165], v[156:157], v[158:159] neg_lo:[0,0,1] neg_hi:[0,0,1]
	v_pk_fma_f32 v[158:159], v[162:163], v[154:155], v[174:175] neg_lo:[0,0,1] neg_hi:[0,0,1]
	v_pk_mul_f32 v[164:165], v[164:165], v[172:173]
	v_pk_mul_f32 v[162:163], v[162:163], v[170:171]
	v_pk_fma_f32 v[156:157], v[168:169], v[156:157], v[164:165]
	v_pk_fma_f32 v[154:155], v[166:167], v[154:155], v[162:163]
	v_subrev_u32_e32 v245, s100, v192
	ds_read_b128 v[162:165], v245
	ds_read_b128 v[166:169], v245 offset:4096
	s_waitcnt lgkmcnt(0)
	v_pk_mul_f32 v[170:171], v[148:149], v[168:169]
	v_pk_mul_f32 v[174:175], v[146:147], v[166:167]
	v_pk_fma_f32 v[172:173], v[152:153], v[164:165], v[170:171] neg_lo:[0,0,1] neg_hi:[0,0,1]
	v_pk_fma_f32 v[170:171], v[150:151], v[162:163], v[174:175] neg_lo:[0,0,1] neg_hi:[0,0,1]
	v_pk_mul_f32 v[152:153], v[152:153], v[168:169]
	v_pk_mul_f32 v[150:151], v[150:151], v[166:167]
	v_pk_fma_f32 v[176:177], v[148:149], v[164:165], v[152:153]
	v_pk_fma_f32 v[174:175], v[146:147], v[162:163], v[150:151]

.LBB0_638:
	s_ashr_i32 s0, s36, 2
	s_ashr_i32 s1, s0, 31
	v_lshl_add_u64 v[158:159], s[0:1], 2, v[190:191]
	v_subrev_u32_e32 v158, s100, v158
	ds_read_b128 v[154:157], v158
	ds_read_b128 v[170:173], v158 offset:4096
	s_waitcnt lgkmcnt(0)
	v_pk_mul_f32 v[158:159], v[168:169], v[172:173]
	v_pk_mul_f32 v[174:175], v[166:167], v[170:171]
	v_pk_fma_f32 v[160:161], v[164:165], v[156:157], v[158:159] neg_lo:[0,0,1] neg_hi:[0,0,1]
	v_pk_fma_f32 v[158:159], v[162:163], v[154:155], v[174:175] neg_lo:[0,0,1] neg_hi:[0,0,1]
	v_pk_mul_f32 v[164:165], v[164:165], v[172:173]
	v_pk_mul_f32 v[162:163], v[162:163], v[170:171]
	v_pk_fma_f32 v[156:157], v[168:169], v[156:157], v[164:165]
	v_pk_fma_f32 v[154:155], v[166:167], v[154:155], v[162:163]
	v_subrev_u32_e32 v245, s100, v196
	ds_read_b128 v[162:165], v245
	ds_read_b128 v[166:169], v245 offset:4096
	s_waitcnt lgkmcnt(0)
	v_pk_mul_f32 v[170:171], v[148:149], v[168:169]
	v_pk_mul_f32 v[174:175], v[146:147], v[166:167]
	v_pk_fma_f32 v[172:173], v[152:153], v[164:165], v[170:171] neg_lo:[0,0,1] neg_hi:[0,0,1]
	v_pk_fma_f32 v[170:171], v[150:151], v[162:163], v[174:175] neg_lo:[0,0,1] neg_hi:[0,0,1]
	v_pk_mul_f32 v[152:153], v[152:153], v[168:169]
	v_pk_mul_f32 v[150:151], v[150:151], v[166:167]
	v_pk_fma_f32 v[176:177], v[148:149], v[164:165], v[152:153]
	v_pk_fma_f32 v[174:175], v[146:147], v[162:163], v[150:151]

.LBB0_646:
	s_ashr_i32 s0, s36, 2
	s_ashr_i32 s1, s0, 31
	v_lshl_add_u64 v[158:159], s[0:1], 2, v[190:191]
	v_subrev_u32_e32 v158, s100, v158
	ds_read_b128 v[154:157], v158
	ds_read_b128 v[170:173], v158 offset:4096
	s_waitcnt lgkmcnt(0)
	v_pk_mul_f32 v[158:159], v[168:169], v[172:173]
	v_pk_mul_f32 v[174:175], v[166:167], v[170:171]
	v_pk_fma_f32 v[160:161], v[164:165], v[156:157], v[158:159] neg_lo:[0,0,1] neg_hi:[0,0,1]
	v_pk_fma_f32 v[158:159], v[162:163], v[154:155], v[174:175] neg_lo:[0,0,1] neg_hi:[0,0,1]
	v_pk_mul_f32 v[164:165], v[164:165], v[172:173]
	v_pk_mul_f32 v[162:163], v[162:163], v[170:171]
	v_pk_fma_f32 v[156:157], v[168:169], v[156:157], v[164:165]
	v_pk_fma_f32 v[154:155], v[166:167], v[154:155], v[162:163]
	v_subrev_u32_e32 v245, s100, v200
	ds_read_b128 v[162:165], v245
	ds_read_b128 v[166:169], v245 offset:4096
	s_waitcnt lgkmcnt(0)
	v_pk_mul_f32 v[170:171], v[148:149], v[168:169]
	v_pk_mul_f32 v[174:175], v[146:147], v[166:167]
	v_pk_fma_f32 v[172:173], v[152:153], v[164:165], v[170:171] neg_lo:[0,0,1] neg_hi:[0,0,1]
	v_pk_fma_f32 v[170:171], v[150:151], v[162:163], v[174:175] neg_lo:[0,0,1] neg_hi:[0,0,1]
	v_pk_mul_f32 v[152:153], v[152:153], v[168:169]
	v_pk_mul_f32 v[150:151], v[150:151], v[166:167]
	v_pk_fma_f32 v[176:177], v[148:149], v[164:165], v[152:153]
	v_pk_fma_f32 v[174:175], v[146:147], v[162:163], v[150:151]

	.amdhsa_kernel _Z10fwd_kernel4Args
		.amdhsa_group_segment_fixed_size 11264
		.amdhsa_private_segment_fixed_size 0
		.amdhsa_kernarg_size 464
		.amdhsa_user_sgpr_count 2
		.amdhsa_user_sgpr_dispatch_ptr 0
		.amdhsa_user_sgpr_queue_ptr 0
		.amdhsa_user_sgpr_kernarg_segment_ptr 1
		.amdhsa_user_sgpr_dispatch_id 0
		.amdhsa_user_sgpr_kernarg_preload_length 0
		.amdhsa_user_sgpr_kernarg_preload_offset 0
		.amdhsa_user_sgpr_private_segment_size 0
		.amdhsa_uses_dynamic_stack 0
		.amdhsa_enable_private_segment 0
		.amdhsa_system_sgpr_workgroup_id_x 1
		.amdhsa_system_sgpr_workgroup_id_y 0
		.amdhsa_system_sgpr_workgroup_id_z 0
		.amdhsa_system_sgpr_workgroup_info 0
		.amdhsa_system_vgpr_workitem_id 2
		.amdhsa_next_free_vgpr 256
		.amdhsa_next_free_sgpr 102
		.amdhsa_accum_offset 256
		.amdhsa_reserve_vcc 1
		.amdhsa_float_round_mode_32 0
		.amdhsa_float_round_mode_16_64 0
		.amdhsa_float_denorm_mode_32 3
		.amdhsa_float_denorm_mode_16_64 3
		.amdhsa_dx10_clamp 1
		.amdhsa_ieee_mode 1
		.amdhsa_fp16_overflow 0
		.amdhsa_tg_split 0
		.amdhsa_exception_fp_ieee_invalid_op 0
		.amdhsa_exception_fp_denorm_src 0
		.amdhsa_exception_fp_ieee_div_zero 0
		.amdhsa_exception_fp_ieee_overflow 0
		.amdhsa_exception_fp_ieee_underflow 0
		.amdhsa_exception_fp_ieee_inexact 0
		.amdhsa_exception_int_div_zero 0
	.end_amdhsa_kernel

amdhsa.kernels:
  - .agpr_count:     0
    .args:
      - .offset:         0
        .size:           208
        .value_kind:     by_value
      - .offset:         208
        .size:           4
        .value_kind:     hidden_block_count_x
      - .offset:         212
        .size:           4
        .value_kind:     hidden_block_count_y
      - .offset:         216
        .size:           4
        .value_kind:     hidden_block_count_z
      - .offset:         220
        .size:           2
        .value_kind:     hidden_group_size_x
      - .offset:         222
        .size:           2
        .value_kind:     hidden_group_size_y
      - .offset:         224
        .size:           2
        .value_kind:     hidden_group_size_z
      - .offset:         226
        .size:           2
        .value_kind:     hidden_remainder_x
      - .offset:         228
        .size:           2
        .value_kind:     hidden_remainder_y
      - .offset:         230
        .size:           2
        .value_kind:     hidden_remainder_z
      - .offset:         248
        .size:           8
        .value_kind:     hidden_global_offset_x
      - .offset:         256
        .size:           8
        .value_kind:     hidden_global_offset_y
      - .offset:         264
        .size:           8
        .value_kind:     hidden_global_offset_z
      - .offset:         272
        .size:           2
        .value_kind:     hidden_grid_dims
      - .offset:         296
        .size:           8
        .value_kind:     hidden_multigrid_sync_arg
      - .offset:         328
        .size:           4
        .value_kind:     hidden_dynamic_lds_size
    .group_segment_fixed_size: 11264
    .kernarg_segment_align: 8
    .kernarg_segment_size: 464
    .language:       OpenCL C
    .language_version:
      - 2
      - 0
    .max_flat_workgroup_size: 512
    .name:           _Z10fwd_kernel4Args
    .private_segment_fixed_size: 0
    .sgpr_count:     108
    .sgpr_spill_count: 124
    .symbol:         _Z10fwd_kernel4Args.kd
    .uniform_work_group_size: 1
    .uses_dynamic_stack: false
    .vgpr_count:     256
    .vgpr_spill_count: 0
    .wavefront_size: 64
